# ctx_slice_gemm K loops (out-proj and FFN-down context slices) rewritten: global loads software-pipelined 2 steps ahead with counted vmcnt instead of a vmcnt(0) after each load
# baseline (speedup 1.0000x reference)
; #define LAS __attribute__((address_space(3)))
; #define LAS __attribute__((address_space(3)))
; __device__ __forceinline__ void ctx_slice_gemm(LAS unsigned char* lds, const bf16_t* A  , const bf16_t* Bt  , int K, ...
;     ...
;     const bf16_t* ap = A + (size_t)(MLAT + row0 + r16) * K + kbeg + 8 * g4;
;     const bf16_t* bp = Bt + (size_t)(col0 + r16) * K + kbeg + 8 * g4;
;     const size_t a16 = (size_t)16 * K;
;     f32x4 acc[4][2];
; #pragma unroll
;     for (int i = 0; i < 4; ++i)
; #pragma unroll
;         for (int j = 0; j < 2; ++j) acc[i][j] = (f32x4){0.f, 0.f, 0.f, 0.f};
; #pragma unroll 4
;     for (int k = 0; k < kw; k += 32) {
;         bf16x8 fa[4], fb[2];
; #pragma unroll
;         for (int i = 0; i < 4; ++i) fa[i] = *(const bf16x8*)(ap + i * a16 + k);
; #pragma unroll
;         for (int j = 0; j < 2; ++j) fb[j] = *(const bf16x8*)(bp + j * a16 + k);
; #pragma unroll
;         for (int i = 0; i < 4; ++i)
; #pragma unroll
;             for (int j = 0; j < 2; ++j) acc[i][j] = __builtin_amdgcn_mfma_f32_16x16x32_bf16(fa[i], fb[j], acc[i][j], 0, 0, 0);
;     }
;     LAS float* part = (LAS float*)lds;
; #pragma unroll
;     for (int i = 0; i < 4; ++i)
; #pragma unroll
;         for (int j = 0; j < 2; ++j)
; #pragma unroll
;             for (int q = 0; q < 4; ++q) part[((wid * 8 + i * 2 + j) * 4 + q) * 64 + lane] = acc[i][j][q];
;     __syncthreads();
;     {
;         const int t = wid, rgi = t >> 1, cg = t & 1, col = col0 + 16 * cg + r16;
;         const float gt = gate2[col];
;         const bool nxt = ng != nullptr;
;         const float gs = nxt ? ng[col] * (1.f + nsc2[col]) : 0.f;
.LBB0_1010:
	v_mov_b32_e32 v5, v222
	s_and_b32 s5, s17, 0xffffffc0
	s_add_i32 s7, s5, 0x4000
	v_readfirstlane_b32 s4, v5
	v_and_b32_e32 v4, 15, v5
	s_ashr_i32 s14, s4, 6
	v_or_b32_e32 v0, s7, v4
	s_and_b32 s6, s16, 0x3e0
	s_lshl_b32 s30, s14, 7
	s_waitcnt lgkmcnt(0)
	v_ashrrev_i32_e32 v1, 31, v0
	s_ashr_i32 s31, s30, 31
	v_or_b32_e32 v2, s6, v4
	v_lshlrev_b64 v[0:1], 11, v[0:1]
	v_lshlrev_b32_e32 v176, 11, v2
	s_lshl_b64 s[30:31], s[30:31], 1
	v_lshl_add_u64 v[0:1], s[0:1], 0, v[0:1]
	v_lshl_add_u64 v[2:3], s[18:19], 0, v[176:177]
	v_and_b32_e32 v176, 48, v5
	v_lshl_add_u64 v[0:1], v[0:1], 0, s[30:31]
	v_lshl_add_u64 v[54:55], v[0:1], 0, v[176:177]
	v_lshl_add_u64 v[0:1], v[2:3], 0, s[30:31]
	v_lshl_add_u64 v[2:3], v[0:1], 0, v[176:177]
	v_add_co_u32_e32 v58, vcc, s87, v2
	s_mov_b32 s7, 0x10000
	s_nop 0
	v_addc_co_u32_e32 v59, vcc, 0, v3, vcc
	v_add_co_u32_e32 v60, vcc, s87, v54
	s_nop 1
	v_addc_co_u32_e32 v61, vcc, 0, v55, vcc
	v_add_co_u32_e32 v62, vcc, s7, v54
	s_mov_b32 s7, 0x18000
	s_nop 1
	v_addc_co_u32_e32 v63, vcc, 0, v55, vcc
	v_add_co_u32_e32 v0, vcc, s7, v54
	s_nop 1
	v_addc_co_u32_e32 v1, vcc, 0, v55, vcc
	s_lshl_b32 s7, s14, 4
	s_and_b32 s7, s7, 16
	s_or_b32 s6, s6, s7
	s_andn2_b64 vcc, exec, s[82:83]
	global_load_dwordx4 v[80:83], v[54:55], off
	global_load_dwordx4 v[84:87], v[60:61], off
	global_load_dwordx4 v[88:91], v[62:63], off
	global_load_dwordx4 v[92:95], v[0:1], off
	global_load_dwordx4 v[96:99], v[2:3], off
	global_load_dwordx4 v[100:103], v[58:59], off
	global_load_dwordx4 v[104:107], v[54:55], off offset:64
	global_load_dwordx4 v[108:111], v[60:61], off offset:64
	global_load_dwordx4 v[112:115], v[62:63], off offset:64
	global_load_dwordx4 v[116:119], v[0:1], off offset:64
	global_load_dwordx4 v[120:123], v[2:3], off offset:64
	global_load_dwordx4 v[124:127], v[58:59], off offset:64
	global_load_dwordx4 v[128:131], v[54:55], off offset:128
	global_load_dwordx4 v[132:135], v[60:61], off offset:128
	global_load_dwordx4 v[136:139], v[62:63], off offset:128
	global_load_dwordx4 v[140:143], v[0:1], off offset:128
	global_load_dwordx4 v[144:147], v[2:3], off offset:128
	global_load_dwordx4 v[148:151], v[58:59], off offset:128
	s_waitcnt vmcnt(12)
	v_mfma_f32_16x16x32_bf16 v[6:9], v[80:83], v[96:99], 0
	v_mfma_f32_16x16x32_bf16 v[10:13], v[80:83], v[100:103], 0
	v_mfma_f32_16x16x32_bf16 v[14:17], v[84:87], v[96:99], 0
	v_mfma_f32_16x16x32_bf16 v[18:21], v[84:87], v[100:103], 0
	v_mfma_f32_16x16x32_bf16 v[22:25], v[88:91], v[96:99], 0
	v_mfma_f32_16x16x32_bf16 v[26:29], v[88:91], v[100:103], 0
	v_mfma_f32_16x16x32_bf16 v[30:33], v[92:95], v[96:99], 0
	v_mfma_f32_16x16x32_bf16 v[34:37], v[92:95], v[100:103], 0
	global_load_dwordx4 v[80:83], v[54:55], off offset:192
	global_load_dwordx4 v[84:87], v[60:61], off offset:192
	global_load_dwordx4 v[88:91], v[62:63], off offset:192
	global_load_dwordx4 v[92:95], v[0:1], off offset:192
	global_load_dwordx4 v[96:99], v[2:3], off offset:192
	global_load_dwordx4 v[100:103], v[58:59], off offset:192
	s_waitcnt vmcnt(12)
	v_mfma_f32_16x16x32_bf16 v[6:9], v[104:107], v[120:123], v[6:9]
	v_mfma_f32_16x16x32_bf16 v[10:13], v[104:107], v[124:127], v[10:13]
	v_mfma_f32_16x16x32_bf16 v[14:17], v[108:111], v[120:123], v[14:17]
	v_mfma_f32_16x16x32_bf16 v[18:21], v[108:111], v[124:127], v[18:21]
	v_mfma_f32_16x16x32_bf16 v[22:25], v[112:115], v[120:123], v[22:25]
	v_mfma_f32_16x16x32_bf16 v[26:29], v[112:115], v[124:127], v[26:29]
	v_mfma_f32_16x16x32_bf16 v[30:33], v[116:119], v[120:123], v[30:33]
	v_mfma_f32_16x16x32_bf16 v[34:37], v[116:119], v[124:127], v[34:37]
	s_waitcnt vmcnt(6)
	v_mfma_f32_16x16x32_bf16 v[6:9], v[128:131], v[144:147], v[6:9]
	v_mfma_f32_16x16x32_bf16 v[10:13], v[128:131], v[148:151], v[10:13]
	v_mfma_f32_16x16x32_bf16 v[14:17], v[132:135], v[144:147], v[14:17]
	v_mfma_f32_16x16x32_bf16 v[18:21], v[132:135], v[148:151], v[18:21]
	v_mfma_f32_16x16x32_bf16 v[22:25], v[136:139], v[144:147], v[22:25]
	v_mfma_f32_16x16x32_bf16 v[26:29], v[136:139], v[148:151], v[26:29]
	v_mfma_f32_16x16x32_bf16 v[30:33], v[140:143], v[144:147], v[30:33]
	v_mfma_f32_16x16x32_bf16 v[34:37], v[140:143], v[148:151], v[34:37]
	s_waitcnt vmcnt(0)
	v_mfma_f32_16x16x32_bf16 v[6:9], v[80:83], v[96:99], v[6:9]
	v_mfma_f32_16x16x32_bf16 v[10:13], v[80:83], v[100:103], v[10:13]
	v_mfma_f32_16x16x32_bf16 v[14:17], v[84:87], v[96:99], v[14:17]
	v_mfma_f32_16x16x32_bf16 v[18:21], v[84:87], v[100:103], v[18:21]
	v_mfma_f32_16x16x32_bf16 v[22:25], v[88:91], v[96:99], v[22:25]
	v_mfma_f32_16x16x32_bf16 v[26:29], v[88:91], v[100:103], v[26:29]
	v_mfma_f32_16x16x32_bf16 v[30:33], v[92:95], v[96:99], v[30:33]
	v_mfma_f32_16x16x32_bf16 v[34:37], v[92:95], v[100:103], v[34:37]
	v_and_b32_e32 v0, 63, v5
	v_lshl_add_u32 v1, v0, 2, 0
	v_lshl_add_u32 v0, s14, 13, v1
	s_nop 7
	ds_write2st64_b32 v0, v6, v7 offset1:1
	ds_write2st64_b32 v0, v8, v9 offset0:2 offset1:3
	ds_write2st64_b32 v0, v10, v11 offset0:4 offset1:5
	ds_write2st64_b32 v0, v12, v13 offset0:6 offset1:7
	ds_write2st64_b32 v0, v14, v15 offset0:8 offset1:9
	ds_write2st64_b32 v0, v16, v17 offset0:10 offset1:11
	ds_write2st64_b32 v0, v18, v19 offset0:12 offset1:13
	ds_write2st64_b32 v0, v20, v21 offset0:14 offset1:15
	ds_write2st64_b32 v0, v22, v23 offset0:16 offset1:17
	ds_write2st64_b32 v0, v24, v25 offset0:18 offset1:19
	ds_write2st64_b32 v0, v26, v27 offset0:20 offset1:21
	ds_write2st64_b32 v0, v28, v29 offset0:22 offset1:23
	ds_write2st64_b32 v0, v30, v31 offset0:24 offset1:25
	ds_write2st64_b32 v0, v32, v33 offset0:26 offset1:27
	ds_write2st64_b32 v0, v34, v35 offset0:28 offset1:29
	ds_write2st64_b32 v0, v36, v37 offset0:30 offset1:31
	v_or_b32_e32 v8, s6, v4
	v_lshlrev_b32_e32 v176, 2, v8
	v_lshl_add_u64 v[2:3], s[8:9], 0, v[176:177]
	s_waitcnt lgkmcnt(0)
	s_barrier
	flat_load_dword v7, v[2:3]
	v_cndmask_b32_e64 v0, 0, 1, s[82:83]
	v_cmp_ne_u32_e64 s[6:7], 1, v0
	s_cbranch_vccnz .LBB0_1012
	v_lshl_add_u64 v[2:3], s[10:11], 0, v[176:177]
	flat_load_dword v0, v[2:3]
	s_nop 0
	global_load_dword v2, v176, s[24:25]
	s_waitcnt vmcnt(0) lgkmcnt(0)
	v_add_f32_e32 v0, 1.0, v0
	v_mul_f32_e32 v6, v2, v0
	s_branch .LBB0_1013

; __device__ __forceinline__ void ctx_slice_gemm(LAS unsigned char* lds, const bf16_t* A  , const bf16_t* Bt  , int K, ...
;     int tid_l = threadIdx.x; asm volatile("" : "+v"(tid_l)); const int tid = tid_l, lane = tid & 63, wid = __builtin_amdgcn_readfirstlane(tid >> 6), r16 = lane & 15, g4 = lane >> 4;
;     const int row0 = (blk >> 5) * 64, col0 = (blk & 31) * 32;
;     const int kw = K >> 3, kbeg = wid * kw;
;     const bf16_t* ap = A + (size_t)(MLAT + row0 + r16) * K + kbeg + 8 * g4;
;     const bf16_t* bp = Bt + (size_t)(col0 + r16) * K + kbeg + 8 * g4;
;     const size_t a16 = (size_t)16 * K;
;     f32x4 acc[4][2];
; #pragma unroll
;     for (int i = 0; i < 4; ++i)
; #pragma unroll
;         for (int j = 0; j < 2; ++j) acc[i][j] = (f32x4){0.f, 0.f, 0.f, 0.f};
; #pragma unroll 4
;     for (int k = 0; k < kw; k += 32) {
;         bf16x8 fa[4], fb[2];
; #pragma unroll
;         for (int i = 0; i < 4; ++i) fa[i] = *(const bf16x8*)(ap + i * a16 + k);
; #pragma unroll
;         for (int j = 0; j < 2; ++j) fb[j] = *(const bf16x8*)(bp + j * a16 + k);
; #pragma unroll
;         for (int i = 0; i < 4; ++i)
; #pragma unroll
;             for (int j = 0; j < 2; ++j) acc[i][j] = __builtin_amdgcn_mfma_f32_16x16x32_bf16(fa[i], fb[j], acc[i][j], 0, 0, 0);
.LBB0_1277:
	v_mov_b32_e32 v61, v222
	s_and_b32 s13, s14, 0x3e0
	v_readfirstlane_b32 s1, v61
	v_and_b32_e32 v60, 15, v61
	s_ashr_i32 s0, s1, 6
	v_or_b32_e32 v0, s13, v60
	s_mul_i32 s26, s0, 0x160
	v_mul_u32_u24_e32 v0, 0xb00, v0
	s_and_b32 s12, s15, 0xffffffc0
	s_ashr_i32 s27, s26, 31
	v_lshlrev_b32_e32 v176, 1, v0
	s_add_i32 s17, s12, 0x4000
	v_lshl_add_u64 v[4:5], s[20:21], 0, v[176:177]
	s_lshl_b64 s[26:27], s[26:27], 1
	v_or_b32_e32 v2, s17, v60
	v_and_b32_e32 v176, 48, v61
	s_waitcnt lgkmcnt(0)
	v_mov_b64_e32 v[0:1], s[18:19]
	v_lshl_add_u64 v[4:5], v[4:5], 0, s[26:27]
	v_mad_i64_i32 v[0:1], s[28:29], v2, s3, v[0:1]
	v_lshl_add_u64 v[24:25], v[4:5], 0, v[176:177]
	v_lshl_add_u64 v[0:1], v[0:1], 0, s[26:27]
	v_add_co_u32_e32 v54, vcc, s30, v24
	v_lshl_add_u64 v[50:51], v[0:1], 0, v[176:177]
	s_nop 0
	v_addc_co_u32_e32 v55, vcc, 0, v25, vcc
	v_add_co_u32_e32 v56, vcc, s30, v50
	s_mov_b32 s17, 0x2c000
	s_nop 0
	v_addc_co_u32_e32 v57, vcc, 0, v51, vcc
	v_add_co_u32_e32 v58, vcc, s17, v50
	s_mov_b32 s17, 0x42000
	s_nop 0
	v_addc_co_u32_e32 v59, vcc, 0, v51, vcc
	v_add_co_u32_e32 v52, vcc, s17, v50
	s_nop 1
	v_addc_co_u32_e32 v53, vcc, 0, v51, vcc
	s_lshl_b32 s17, s0, 4
	s_and_b32 s17, s17, 16
	s_or_b32 s13, s13, s17
	s_ashr_i32 s1, s1, 3
	s_and_b32 s1, s1, -16
	s_add_i32 s1, s1, s12
	s_brev_b32 s12, 64
	global_load_dwordx4 v[80:83], v[50:51], off
	global_load_dwordx4 v[84:87], v[56:57], off
	global_load_dwordx4 v[88:91], v[58:59], off
	global_load_dwordx4 v[92:95], v[52:53], off
	global_load_dwordx4 v[96:99], v[24:25], off
	global_load_dwordx4 v[100:103], v[54:55], off
	global_load_dwordx4 v[104:107], v[50:51], off offset:64
	global_load_dwordx4 v[108:111], v[56:57], off offset:64
	global_load_dwordx4 v[112:115], v[58:59], off offset:64
	global_load_dwordx4 v[116:119], v[52:53], off offset:64
	global_load_dwordx4 v[120:123], v[24:25], off offset:64
	global_load_dwordx4 v[124:127], v[54:55], off offset:64
	global_load_dwordx4 v[128:131], v[50:51], off offset:128
	global_load_dwordx4 v[132:135], v[56:57], off offset:128
	global_load_dwordx4 v[136:139], v[58:59], off offset:128
	global_load_dwordx4 v[140:143], v[52:53], off offset:128
	global_load_dwordx4 v[144:147], v[24:25], off offset:128
	global_load_dwordx4 v[148:151], v[54:55], off offset:128
	s_waitcnt vmcnt(12)
	v_mfma_f32_16x16x32_bf16 v[62:65], v[80:83], v[96:99], 0
	v_mfma_f32_16x16x32_bf16 v[66:69], v[80:83], v[100:103], 0
	v_mfma_f32_16x16x32_bf16 v[70:73], v[84:87], v[96:99], 0
	v_mfma_f32_16x16x32_bf16 v[74:77], v[84:87], v[100:103], 0
	v_mfma_f32_16x16x32_bf16 v[26:29], v[88:91], v[96:99], 0
	v_mfma_f32_16x16x32_bf16 v[30:33], v[88:91], v[100:103], 0
	v_mfma_f32_16x16x32_bf16 v[34:37], v[92:95], v[96:99], 0
	v_mfma_f32_16x16x32_bf16 v[38:41], v[92:95], v[100:103], 0
	global_load_dwordx4 v[80:83], v[50:51], off offset:192
	global_load_dwordx4 v[84:87], v[56:57], off offset:192
	global_load_dwordx4 v[88:91], v[58:59], off offset:192
	global_load_dwordx4 v[92:95], v[52:53], off offset:192
	global_load_dwordx4 v[96:99], v[24:25], off offset:192
	global_load_dwordx4 v[100:103], v[54:55], off offset:192
	s_waitcnt vmcnt(12)
	v_mfma_f32_16x16x32_bf16 v[62:65], v[104:107], v[120:123], v[62:65]
	v_mfma_f32_16x16x32_bf16 v[66:69], v[104:107], v[124:127], v[66:69]
	v_mfma_f32_16x16x32_bf16 v[70:73], v[108:111], v[120:123], v[70:73]
	v_mfma_f32_16x16x32_bf16 v[74:77], v[108:111], v[124:127], v[74:77]
	v_mfma_f32_16x16x32_bf16 v[26:29], v[112:115], v[120:123], v[26:29]
	v_mfma_f32_16x16x32_bf16 v[30:33], v[112:115], v[124:127], v[30:33]
	v_mfma_f32_16x16x32_bf16 v[34:37], v[116:119], v[120:123], v[34:37]
	v_mfma_f32_16x16x32_bf16 v[38:41], v[116:119], v[124:127], v[38:41]
	global_load_dwordx4 v[104:107], v[50:51], off offset:256
	global_load_dwordx4 v[108:111], v[56:57], off offset:256
	global_load_dwordx4 v[112:115], v[58:59], off offset:256
	global_load_dwordx4 v[116:119], v[52:53], off offset:256
	global_load_dwordx4 v[120:123], v[24:25], off offset:256
	global_load_dwordx4 v[124:127], v[54:55], off offset:256
	s_waitcnt vmcnt(12)
	v_mfma_f32_16x16x32_bf16 v[62:65], v[128:131], v[144:147], v[62:65]
	v_mfma_f32_16x16x32_bf16 v[66:69], v[128:131], v[148:151], v[66:69]
	v_mfma_f32_16x16x32_bf16 v[70:73], v[132:135], v[144:147], v[70:73]
	v_mfma_f32_16x16x32_bf16 v[74:77], v[132:135], v[148:151], v[74:77]
	v_mfma_f32_16x16x32_bf16 v[26:29], v[136:139], v[144:147], v[26:29]
	v_mfma_f32_16x16x32_bf16 v[30:33], v[136:139], v[148:151], v[30:33]
	v_mfma_f32_16x16x32_bf16 v[34:37], v[140:143], v[144:147], v[34:37]
	v_mfma_f32_16x16x32_bf16 v[38:41], v[140:143], v[148:151], v[38:41]
	global_load_dwordx4 v[128:131], v[50:51], off offset:320
	global_load_dwordx4 v[132:135], v[56:57], off offset:320
	global_load_dwordx4 v[136:139], v[58:59], off offset:320
	global_load_dwordx4 v[140:143], v[52:53], off offset:320
	global_load_dwordx4 v[144:147], v[24:25], off offset:320
	global_load_dwordx4 v[148:151], v[54:55], off offset:320
	s_waitcnt vmcnt(12)
	v_mfma_f32_16x16x32_bf16 v[62:65], v[80:83], v[96:99], v[62:65]
	v_mfma_f32_16x16x32_bf16 v[66:69], v[80:83], v[100:103], v[66:69]
	v_mfma_f32_16x16x32_bf16 v[70:73], v[84:87], v[96:99], v[70:73]
	v_mfma_f32_16x16x32_bf16 v[74:77], v[84:87], v[100:103], v[74:77]
	v_mfma_f32_16x16x32_bf16 v[26:29], v[88:91], v[96:99], v[26:29]
	v_mfma_f32_16x16x32_bf16 v[30:33], v[88:91], v[100:103], v[30:33]
	v_mfma_f32_16x16x32_bf16 v[34:37], v[92:95], v[96:99], v[34:37]
	v_mfma_f32_16x16x32_bf16 v[38:41], v[92:95], v[100:103], v[38:41]
	global_load_dwordx4 v[80:83], v[50:51], off offset:384
	global_load_dwordx4 v[84:87], v[56:57], off offset:384
	global_load_dwordx4 v[88:91], v[58:59], off offset:384
	global_load_dwordx4 v[92:95], v[52:53], off offset:384
	global_load_dwordx4 v[96:99], v[24:25], off offset:384
	global_load_dwordx4 v[100:103], v[54:55], off offset:384
	s_waitcnt vmcnt(12)
; #define LAS __attribute__((address_space(3)))
; #define LAS __attribute__((address_space(3)))
; __device__ __forceinline__ void ctx_slice_gemm(LAS unsigned char* lds, const bf16_t* A  , const bf16_t* Bt  , int K, ...
;     ...
;     for (int k = 0; k < kw; k += 32) {
;         bf16x8 fa[4], fb[2];
; #pragma unroll
;         for (int i = 0; i < 4; ++i) fa[i] = *(const bf16x8*)(ap + i * a16 + k);
; #pragma unroll
;         for (int j = 0; j < 2; ++j) fb[j] = *(const bf16x8*)(bp + j * a16 + k);
; #pragma unroll
;         for (int i = 0; i < 4; ++i)
; #pragma unroll
;             for (int j = 0; j < 2; ++j) acc[i][j] = __builtin_amdgcn_mfma_f32_16x16x32_bf16(fa[i], fb[j], acc[i][j], 0, 0, 0);
;     }
;     LAS float* part = (LAS float*)lds;
; #pragma unroll
;     for (int i = 0; i < 4; ++i)
; #pragma unroll
;         for (int j = 0; j < 2; ++j)
; #pragma unroll
;             for (int q = 0; q < 4; ++q) part[((wid * 8 + i * 2 + j) * 4 + q) * 64 + lane] = acc[i][j][q];
;     __syncthreads();
	v_mfma_f32_16x16x32_bf16 v[62:65], v[104:107], v[120:123], v[62:65]
	v_mfma_f32_16x16x32_bf16 v[66:69], v[104:107], v[124:127], v[66:69]
	v_mfma_f32_16x16x32_bf16 v[70:73], v[108:111], v[120:123], v[70:73]
	v_mfma_f32_16x16x32_bf16 v[74:77], v[108:111], v[124:127], v[74:77]
	v_mfma_f32_16x16x32_bf16 v[26:29], v[112:115], v[120:123], v[26:29]
	v_mfma_f32_16x16x32_bf16 v[30:33], v[112:115], v[124:127], v[30:33]
	v_mfma_f32_16x16x32_bf16 v[34:37], v[116:119], v[120:123], v[34:37]
	v_mfma_f32_16x16x32_bf16 v[38:41], v[116:119], v[124:127], v[38:41]
	global_load_dwordx4 v[104:107], v[50:51], off offset:448
	global_load_dwordx4 v[108:111], v[56:57], off offset:448
	global_load_dwordx4 v[112:115], v[58:59], off offset:448
	global_load_dwordx4 v[116:119], v[52:53], off offset:448
	global_load_dwordx4 v[120:123], v[24:25], off offset:448
	global_load_dwordx4 v[124:127], v[54:55], off offset:448
	s_waitcnt vmcnt(12)
	v_mfma_f32_16x16x32_bf16 v[62:65], v[128:131], v[144:147], v[62:65]
	v_mfma_f32_16x16x32_bf16 v[66:69], v[128:131], v[148:151], v[66:69]
	v_mfma_f32_16x16x32_bf16 v[70:73], v[132:135], v[144:147], v[70:73]
	v_mfma_f32_16x16x32_bf16 v[74:77], v[132:135], v[148:151], v[74:77]
	v_mfma_f32_16x16x32_bf16 v[26:29], v[136:139], v[144:147], v[26:29]
	v_mfma_f32_16x16x32_bf16 v[30:33], v[136:139], v[148:151], v[30:33]
	v_mfma_f32_16x16x32_bf16 v[34:37], v[140:143], v[144:147], v[34:37]
	v_mfma_f32_16x16x32_bf16 v[38:41], v[140:143], v[148:151], v[38:41]
	global_load_dwordx4 v[128:131], v[50:51], off offset:512
	global_load_dwordx4 v[132:135], v[56:57], off offset:512
	global_load_dwordx4 v[136:139], v[58:59], off offset:512
	global_load_dwordx4 v[140:143], v[52:53], off offset:512
	global_load_dwordx4 v[144:147], v[24:25], off offset:512
	global_load_dwordx4 v[148:151], v[54:55], off offset:512
	s_waitcnt vmcnt(12)
	v_mfma_f32_16x16x32_bf16 v[62:65], v[80:83], v[96:99], v[62:65]
	v_mfma_f32_16x16x32_bf16 v[66:69], v[80:83], v[100:103], v[66:69]
	v_mfma_f32_16x16x32_bf16 v[70:73], v[84:87], v[96:99], v[70:73]
	v_mfma_f32_16x16x32_bf16 v[74:77], v[84:87], v[100:103], v[74:77]
	v_mfma_f32_16x16x32_bf16 v[26:29], v[88:91], v[96:99], v[26:29]
	v_mfma_f32_16x16x32_bf16 v[30:33], v[88:91], v[100:103], v[30:33]
	v_mfma_f32_16x16x32_bf16 v[34:37], v[92:95], v[96:99], v[34:37]
	v_mfma_f32_16x16x32_bf16 v[38:41], v[92:95], v[100:103], v[38:41]
	global_load_dwordx4 v[80:83], v[50:51], off offset:576
	global_load_dwordx4 v[84:87], v[56:57], off offset:576
	global_load_dwordx4 v[88:91], v[58:59], off offset:576
	global_load_dwordx4 v[92:95], v[52:53], off offset:576
	global_load_dwordx4 v[96:99], v[24:25], off offset:576
	global_load_dwordx4 v[100:103], v[54:55], off offset:576
	s_waitcnt vmcnt(12)
	v_mfma_f32_16x16x32_bf16 v[62:65], v[104:107], v[120:123], v[62:65]
	v_mfma_f32_16x16x32_bf16 v[66:69], v[104:107], v[124:127], v[66:69]
	v_mfma_f32_16x16x32_bf16 v[70:73], v[108:111], v[120:123], v[70:73]
	v_mfma_f32_16x16x32_bf16 v[74:77], v[108:111], v[124:127], v[74:77]
	v_mfma_f32_16x16x32_bf16 v[26:29], v[112:115], v[120:123], v[26:29]
	v_mfma_f32_16x16x32_bf16 v[30:33], v[112:115], v[124:127], v[30:33]
	v_mfma_f32_16x16x32_bf16 v[34:37], v[116:119], v[120:123], v[34:37]
	v_mfma_f32_16x16x32_bf16 v[38:41], v[116:119], v[124:127], v[38:41]
	global_load_dwordx4 v[104:107], v[50:51], off offset:640
	global_load_dwordx4 v[108:111], v[56:57], off offset:640
	global_load_dwordx4 v[112:115], v[58:59], off offset:640
	global_load_dwordx4 v[116:119], v[52:53], off offset:640
	global_load_dwordx4 v[120:123], v[24:25], off offset:640
	global_load_dwordx4 v[124:127], v[54:55], off offset:640
	s_waitcnt vmcnt(12)
	v_mfma_f32_16x16x32_bf16 v[62:65], v[128:131], v[144:147], v[62:65]
	v_mfma_f32_16x16x32_bf16 v[66:69], v[128:131], v[148:151], v[66:69]
	v_mfma_f32_16x16x32_bf16 v[70:73], v[132:135], v[144:147], v[70:73]
	v_mfma_f32_16x16x32_bf16 v[74:77], v[132:135], v[148:151], v[74:77]
	v_mfma_f32_16x16x32_bf16 v[26:29], v[136:139], v[144:147], v[26:29]
	v_mfma_f32_16x16x32_bf16 v[30:33], v[136:139], v[148:151], v[30:33]
	v_mfma_f32_16x16x32_bf16 v[34:37], v[140:143], v[144:147], v[34:37]
	v_mfma_f32_16x16x32_bf16 v[38:41], v[140:143], v[148:151], v[38:41]
	s_waitcnt vmcnt(6)
	v_mfma_f32_16x16x32_bf16 v[62:65], v[80:83], v[96:99], v[62:65]
	v_mfma_f32_16x16x32_bf16 v[66:69], v[80:83], v[100:103], v[66:69]
	v_mfma_f32_16x16x32_bf16 v[70:73], v[84:87], v[96:99], v[70:73]
	v_mfma_f32_16x16x32_bf16 v[74:77], v[84:87], v[100:103], v[74:77]
	v_mfma_f32_16x16x32_bf16 v[26:29], v[88:91], v[96:99], v[26:29]
	v_mfma_f32_16x16x32_bf16 v[30:33], v[88:91], v[100:103], v[30:33]
	v_mfma_f32_16x16x32_bf16 v[34:37], v[92:95], v[96:99], v[34:37]
	v_mfma_f32_16x16x32_bf16 v[38:41], v[92:95], v[100:103], v[38:41]
	s_waitcnt vmcnt(0)
	v_mfma_f32_16x16x32_bf16 v[62:65], v[104:107], v[120:123], v[62:65]
	v_mfma_f32_16x16x32_bf16 v[66:69], v[104:107], v[124:127], v[66:69]
	v_mfma_f32_16x16x32_bf16 v[70:73], v[108:111], v[120:123], v[70:73]
	v_mfma_f32_16x16x32_bf16 v[74:77], v[108:111], v[124:127], v[74:77]
	v_mfma_f32_16x16x32_bf16 v[26:29], v[112:115], v[120:123], v[26:29]
	v_mfma_f32_16x16x32_bf16 v[30:33], v[112:115], v[124:127], v[30:33]
	v_mfma_f32_16x16x32_bf16 v[34:37], v[116:119], v[120:123], v[34:37]
	v_mfma_f32_16x16x32_bf16 v[38:41], v[116:119], v[124:127], v[38:41]
	v_and_b32_e32 v52, 63, v61
	v_lshl_add_u32 v52, v52, 2, 0
	v_lshl_add_u32 v53, s0, 13, v52
	v_or_b32_e32 v13, s13, v60
	v_lshlrev_b32_e32 v176, 2, v13
	s_lshl_b32 s0, s0, 10
	v_add_u32_e32 v14, s0, v52
	s_nop 7
	ds_write2st64_b32 v53, v62, v63 offset1:1
	ds_write2st64_b32 v53, v64, v65 offset0:2 offset1:3
	ds_write2st64_b32 v53, v66, v67 offset0:4 offset1:5
	ds_write2st64_b32 v53, v68, v69 offset0:6 offset1:7
	ds_write2st64_b32 v53, v70, v71 offset0:8 offset1:9
	ds_write2st64_b32 v53, v72, v73 offset0:10 offset1:11
	ds_write2st64_b32 v53, v74, v75 offset0:12 offset1:13
	ds_write2st64_b32 v53, v76, v77 offset0:14 offset1:15
	ds_write2st64_b32 v53, v26, v27 offset0:16 offset1:17
	ds_write2st64_b32 v53, v28, v29 offset0:18 offset1:19
	ds_write2st64_b32 v53, v30, v31 offset0:20 offset1:21
	ds_write2st64_b32 v53, v32, v33 offset0:22 offset1:23
	ds_write2st64_b32 v53, v34, v35 offset0:24 offset1:25
	ds_write2st64_b32 v53, v36, v37 offset0:26 offset1:27
	ds_write2st64_b32 v53, v38, v39 offset0:28 offset1:29
	ds_write2st64_b32 v53, v40, v41 offset0:30 offset1:31
	v_lshl_add_u64 v[0:1], s[4:5], 0, v[176:177]
	s_waitcnt lgkmcnt(0)
	s_barrier
; __device__ __forceinline__ unsigned pkbf(float lo, float hi) { return pg8::cvt_pk_bf16(lo, hi); }
; __device__ __forceinline__ void ctx_slice_gemm(LAS unsigned char* lds, const bf16_t* A  , const bf16_t* Bt  , int K, ...
;     ...
;     {
;         const int t = wid, rgi = t >> 1, cg = t & 1, col = col0 + 16 * cg + r16;
;         const float gt = gate2[col];
;         const bool nxt = ng != nullptr;
;         const float gs = nxt ? ng[col] * (1.f + nsc2[col]) : 0.f;
; #pragma unroll
;         for (int q = 0; q < 4; ++q) {
;             float s = 0.f;
; #pragma unroll
;             for (int w = 0; w < 8; ++w) s += part[((w * 8 + t) * 4 + q) * 64 + lane];
;             const int rr = row0 + 16 * rgi + 4 * g4 + q;
;             const float x = res_ctx[(size_t)rr * DM + col] + gt * s;
;             dst_ctx[(size_t)rr * DM + col] = x;
;             if (nxt) {
;                 xg[(size_t)(MLAT + rr) * DM + col] = (bf16_t)(pkbf(x * gs, 0.f) & 0xffffu);
;                 float ss = x * x;
;                 ss += __shfl_xor(ss, 1); ss += __shfl_xor(ss, 2); ss += __shfl_xor(ss, 4); ss += __shfl_xor(ss, 8);
;                 if (r16 == 0) unsafeAtomicAdd(rowsq_next + MLAT + rr, ss);
;             }
	flat_load_dword v8, v[0:1]
	v_lshrrev_b32_e32 v0, 2, v61
	v_and_or_b32 v0, v0, 12, s1
	v_ashrrev_i32_e32 v1, 31, v0
	v_lshlrev_b64 v[2:3], 12, v[0:1]
	v_lshl_add_u64 v[2:3], s[22:23], 0, v[2:3]
	v_lshl_add_u64 v[2:3], v[2:3], 0, v[176:177]
	flat_load_dword v15, v[2:3]
	v_lshl_add_u64 v[4:5], s[8:9], 0, v[176:177]
	flat_load_dword v12, v[4:5]
	global_load_dword v16, v176, s[6:7]
	ds_read2st64_b32 v[4:5], v14 offset1:32
	ds_read2st64_b32 v[6:7], v14 offset0:64 offset1:96
	ds_read2st64_b32 v[10:11], v14 offset0:128 offset1:160
	v_cmp_eq_u32_e64 s[0:1], 0, v60
	s_waitcnt lgkmcnt(0)
	v_add_f32_e32 v4, 0, v4
	v_add_f32_e32 v9, v4, v5
	ds_read2st64_b32 v[4:5], v14 offset0:192 offset1:224
	v_add_f32_e32 v6, v9, v6
	v_add_f32_e32 v6, v6, v7
	v_add_f32_e32 v6, v6, v10
	v_add_f32_e32 v6, v6, v11
	s_waitcnt lgkmcnt(0)
	v_add_f32_e32 v4, v6, v4
	v_and_b32_e32 v6, 64, v229
	v_add_f32_e32 v4, v4, v5
	v_xor_b32_e32 v5, 1, v229
	v_add_u32_e32 v7, 64, v6
	v_cmp_lt_i32_e32 vcc, v5, v7
	s_waitcnt vmcnt(0)
	v_fmac_f32_e32 v15, v8, v4
	v_cndmask_b32_e32 v5, v229, v5, vcc
	v_mul_f32_e32 v4, v15, v15
	v_lshlrev_b32_e32 v9, 2, v5
	ds_bpermute_b32 v6, v9, v4
	v_xor_b32_e32 v5, 2, v229
	v_cmp_lt_i32_e32 vcc, v5, v7
	flat_store_dword v[2:3], v15
	v_xor_b32_e32 v2, 4, v229
	v_cndmask_b32_e32 v5, v229, v5, vcc
	s_waitcnt lgkmcnt(0)
	v_fmac_f32_e32 v6, v15, v15
	v_lshlrev_b32_e32 v10, 2, v5
	ds_bpermute_b32 v11, v10, v6
	v_cmp_lt_i32_e32 vcc, v2, v7
	v_add_f32_e32 v4, 1.0, v12
	v_mul_f32_e32 v12, v16, v4
	v_cndmask_b32_e32 v2, v229, v2, vcc
	s_waitcnt lgkmcnt(0)
	v_add_f32_e32 v6, v6, v11
	v_lshlrev_b32_e32 v11, 2, v2
	v_lshlrev_b32_e32 v4, 1, v13
	v_mov_b32_e32 v5, v177
	ds_bpermute_b32 v13, v11, v6
	v_mul_f32_e32 v2, v12, v15
	v_lshl_add_u64 v[4:5], s[24:25], 0, v[4:5]
	v_cvt_pk_bf16_f32 v15, v2, v177
	v_lshlrev_b64 v[2:3], 11, v[0:1]
	v_lshl_add_u64 v[2:3], v[4:5], 0, v[2:3]
	v_xor_b32_e32 v4, 8, v229
	v_cmp_lt_i32_e32 vcc, v4, v7
	s_waitcnt lgkmcnt(0)
	v_add_f32_e32 v6, v6, v13
	v_cndmask_b32_e32 v4, v229, v4, vcc
	v_lshlrev_b32_e32 v13, 2, v4
	ds_bpermute_b32 v7, v13, v6
	v_add_co_u32_e32 v4, vcc, s12, v2
	s_nop 1
	v_addc_co_u32_e32 v5, vcc, 0, v3, vcc
	flat_store_short v[4:5], v15
	s_and_saveexec_b64 s[12:13], s[0:1]
	s_cbranch_execz .LBB0_1279
	s_waitcnt lgkmcnt(0)
	v_add_f32_e32 v15, v6, v7
	v_lshl_add_u64 v[6:7], v[0:1], 2, s[10:11]
	flat_atomic_add_f32 v[6:7], v15
